# up-projection GEMM: first K-loop iteration peeled with waits that cover only its own loads, so the previous tile's epilogue stores drain behind the first MFMA segments
# baseline (speedup 1.0000x reference)
; #define PG8_STAGE(bufoff, gbase, voff) do { _Pragma("unroll") for (int _i = 0; _i < 2; ++_i) \
;         __builtin_amdgcn_global_load_lds((const unsigned*)((const char*)(gbase) + (voff)[_i]), (PG8_LAS unsigned*)(lds + (bufoff) + ldsw + _i * 8192), 16, 0, 0); } while (0)
; #define PG8_LDA(dst, b, h) do { _Pragma("unroll") for (int m = 0; m < 4; ++m) _Pragma("unroll") for (int k = 0; k < 2; ++k) dst[m][k] = *(const PG8_LAS bf16x8*)(lds + PG8_SA(b, h) + aoff + m * 2048 + k * 1024); } while (0)
; #define PG8_LDB(dst, b, h) do { _Pragma("unroll") for (int n = 0; n < 2; ++n) _Pragma("unroll") for (int k = 0; k < 2; ++k) dst[n][k] = *(const PG8_LAS bf16x8*)(lds + PG8_SB(b, h) + boff + n * 2048 + k * 1024); } while (0)
; #define PG8_WAIT_V(n) asm volatile("s_waitcnt vmcnt(" #n ")" ::: "memory")
; #define PG8_WAIT_L(n) asm volatile("s_waitcnt lgkmcnt(" #n ")" ::: "memory")
; #define PG8_BAR __builtin_amdgcn_s_barrier()
; template <class Epi, class Sched, bool ALIGN_EPI = false, bool SP2 = false>
; __device__ __forceinline__ void gemm_phase(PG8_LAS unsigned char* lds, const Gemm g, const Sched& S, const Epi& E) {
;     ...
;         const bool has_next = S.next(ui + 1, nxt);
;         const char* nA = has_next ? (const char*)g.A + S.a_byte(nxt, K) : cA; const char* nB = has_next ? (const char*)g.Bt + (size_t)nxt.pn * tstep : cB;
;         for (int t = 0; t < nt; t += 2) {
;             const bool last = (t == nt - 2);
;             const char* a1 = cA + (size_t)(t + 1) * kstep;
;             const char* a2 = last ? nA : cA + (size_t)(t + 2) * kstep; const char* b2 = last ? nB : cB + (size_t)(t + 2) * kstep;
;             const char* a3 = a2 + kstep; const char* b3 = b2 + kstep;
;             if (last && has_next) S.a_ready(nxt);
;             if constexpr (SP2) {
;             PG8_LDB(B0, 0, 0); PG8_LDB(B1, 0, 1); PG8_SCHED; PG8_LDA(At, 0, 0); PG8_STAGE(PG8_SA(1, 1), a1 + hstep, voffA);
;             PG8_WAIT_V(8); PG8_WAIT_L(0); PG8_BAR; PG8_MMA(0, 0, At, B0); PG8_MMA(0, 1, At, B1); PG8_BAR; PG8_SCHED;
;     ...
; #pragma unroll
;         for (int a = 0; a < 2; ++a)
; #pragma unroll
;             for (int b = 0; b < 2; ++b)
; #pragma unroll
;                 for (int m = 0; m < 4; ++m)
; #pragma unroll
;                     for (int n = 0; n < 2; ++n) acc[a][b][m][n] = (f32x4){0.f, 0.f, 0.f, 0.f};
;         cur = nxt; cA = nA; cB = nB; ++ui;
.LBB0_287:
	s_ashr_i32 s71, s70, 31
	s_lshl_b64 s[6:7], s[70:71], 19
	s_add_u32 s74, s16, s6
	s_addc_u32 s75, s84, s7
	s_and_b64 s[4:5], s[4:5], exec
	s_cselect_b32 s9, s75, s77
	s_cselect_b32 s71, s74, s76
	s_add_u32 s4, s78, 0x40080
	s_addc_u32 s5, s79, 0
	s_add_u32 s78, s76, 0x100
	v_mov_b32_e32 v0, 0
	s_addc_u32 s79, s77, 0
	s_mov_b32 vcc_lo, -2
	v_mov_b32_e32 v1, v0
	v_mov_b32_e32 v2, v0
	v_mov_b32_e32 v3, v0
	v_mov_b32_e32 v4, v0
	v_mov_b32_e32 v5, v0
	v_mov_b32_e32 v6, v0
	v_mov_b32_e32 v7, v0
	v_mov_b32_e32 v16, v0
	v_mov_b32_e32 v17, v0
	v_mov_b32_e32 v18, v0
	v_mov_b32_e32 v19, v0
	v_mov_b32_e32 v20, v0
	v_mov_b32_e32 v21, v0
	v_mov_b32_e32 v22, v0
	v_mov_b32_e32 v23, v0
	v_mov_b32_e32 v32, v0
	v_mov_b32_e32 v33, v0
	v_mov_b32_e32 v34, v0
	v_mov_b32_e32 v35, v0
	v_mov_b32_e32 v36, v0
	v_mov_b32_e32 v37, v0
	v_mov_b32_e32 v38, v0
	v_mov_b32_e32 v39, v0
	v_mov_b32_e32 v48, v0
	v_mov_b32_e32 v49, v0
	v_mov_b32_e32 v50, v0
	v_mov_b32_e32 v51, v0
	v_mov_b32_e32 v52, v0
	v_mov_b32_e32 v53, v0
	v_mov_b32_e32 v54, v0
	v_mov_b32_e32 v55, v0
	v_mov_b32_e32 v8, v0
	v_mov_b32_e32 v9, v0
	v_mov_b32_e32 v10, v0
	v_mov_b32_e32 v11, v0
	v_mov_b32_e32 v12, v0
	v_mov_b32_e32 v13, v0
	v_mov_b32_e32 v14, v0
	v_mov_b32_e32 v15, v0
	v_mov_b32_e32 v24, v0
	v_mov_b32_e32 v25, v0
	v_mov_b32_e32 v26, v0
	v_mov_b32_e32 v27, v0
	v_mov_b32_e32 v28, v0
	v_mov_b32_e32 v29, v0
	v_mov_b32_e32 v30, v0
	v_mov_b32_e32 v31, v0
	v_mov_b32_e32 v40, v0
	v_mov_b32_e32 v41, v0
	v_mov_b32_e32 v42, v0
	v_mov_b32_e32 v43, v0
	v_mov_b32_e32 v44, v0
	v_mov_b32_e32 v45, v0
	v_mov_b32_e32 v46, v0
	v_mov_b32_e32 v47, v0
	v_mov_b32_e32 v56, v0
	v_mov_b32_e32 v57, v0
	v_mov_b32_e32 v58, v0
	v_mov_b32_e32 v59, v0
	v_mov_b32_e32 v60, v0
	v_mov_b32_e32 v61, v0
	v_mov_b32_e32 v62, v0
	v_mov_b32_e32 v63, v0
	v_mov_b32_e32 v80, v0
	v_mov_b32_e32 v81, v0
	v_mov_b32_e32 v82, v0
	v_mov_b32_e32 v83, v0
	v_mov_b32_e32 v84, v0
	v_mov_b32_e32 v85, v0
	v_mov_b32_e32 v86, v0
	v_mov_b32_e32 v87, v0
	v_mov_b32_e32 v112, v0
	v_mov_b32_e32 v113, v0
	v_mov_b32_e32 v114, v0
	v_mov_b32_e32 v115, v0
	v_mov_b32_e32 v116, v0
	v_mov_b32_e32 v117, v0
	v_mov_b32_e32 v118, v0
	v_mov_b32_e32 v119, v0
	v_mov_b32_e32 v128, v0
	v_mov_b32_e32 v129, v0
	v_mov_b32_e32 v130, v0
	v_mov_b32_e32 v131, v0
	v_mov_b32_e32 v132, v0
	v_mov_b32_e32 v133, v0
	v_mov_b32_e32 v134, v0
	v_mov_b32_e32 v135, v0
	v_mov_b32_e32 v144, v0
	v_mov_b32_e32 v145, v0
	v_mov_b32_e32 v146, v0
	v_mov_b32_e32 v147, v0
	v_mov_b32_e32 v148, v0
	v_mov_b32_e32 v149, v0
	v_mov_b32_e32 v150, v0
	v_mov_b32_e32 v151, v0
	v_mov_b32_e32 v104, v0
	v_mov_b32_e32 v105, v0
	v_mov_b32_e32 v106, v0
	v_mov_b32_e32 v107, v0
	v_mov_b32_e32 v108, v0
	v_mov_b32_e32 v109, v0
	v_mov_b32_e32 v110, v0
	v_mov_b32_e32 v111, v0
	v_mov_b32_e32 v120, v0
	v_mov_b32_e32 v121, v0
	v_mov_b32_e32 v122, v0
	v_mov_b32_e32 v123, v0
	v_mov_b32_e32 v124, v0
	v_mov_b32_e32 v125, v0
	v_mov_b32_e32 v126, v0
	v_mov_b32_e32 v127, v0
	v_mov_b32_e32 v136, v0
	v_mov_b32_e32 v137, v0
	v_mov_b32_e32 v138, v0
	v_mov_b32_e32 v139, v0
	v_mov_b32_e32 v140, v0
	v_mov_b32_e32 v141, v0
	v_mov_b32_e32 v142, v0
	v_mov_b32_e32 v143, v0
	v_mov_b32_e32 v152, v0
	v_mov_b32_e32 v153, v0
	v_mov_b32_e32 v154, v0
	v_mov_b32_e32 v155, v0
	v_mov_b32_e32 v156, v0
	v_mov_b32_e32 v157, v0
	v_mov_b32_e32 v158, v0
	v_mov_b32_e32 v159, v0
	s_add_u32 s6, s4, 0xfffc0080
	s_addc_u32 s7, s5, -1
	s_add_i32 s18, 0, 0x10000
	s_cmp_eq_u32 vcc_lo, 12
	s_cselect_b32 s77, s73, s7
	s_cselect_b32 s76, s72, s6
	s_cselect_b32 s7, s9, s79
	s_cselect_b32 s6, s71, s78
	s_add_i32 vcc_hi, 0, 0x14000
	v_add_u32_e32 v76, s18, v196
	v_add_u32_e32 v100, vcc_hi, v196
	ds_read_b128 v[64:67], v76
	ds_read_b128 v[68:71], v76 offset:1024
	ds_read_b128 v[72:75], v76 offset:2048
	ds_read_b128 v[76:79], v76 offset:3072
	ds_read_b128 v[88:91], v100
	ds_read_b128 v[92:95], v100 offset:1024
	ds_read_b128 v[96:99], v100 offset:2048
	ds_read_b128 v[100:103], v100 offset:3072
	v_lshl_add_u64 v[164:165], s[4:5], 0, v[178:179]
	s_add_i32 m0, s91, 0xc000
	ds_read_b128 v[160:163], v218
	ds_read_b128 v[182:185], v218 offset:1024
	ds_read_b128 v[186:189], v218 offset:2048
	ds_read_b128 v[190:193], v218 offset:3072
	ds_read_b128 v[212:215], v218 offset:4096
	ds_read_b128 v[220:223], v218 offset:5120
	ds_read_b128 v[224:227], v218 offset:6144
	ds_read_b128 v[228:231], v218 offset:7168
	global_load_lds_dwordx4 v[164:165], off
	v_lshl_add_u64 v[164:165], s[4:5], 0, v[180:181]
	s_add_i32 m0, s91, 0xe000
	s_nop 0
	global_load_lds_dwordx4 v[164:165], off
	s_waitcnt vmcnt(63)
	s_waitcnt lgkmcnt(0)
	s_barrier
; #define PG8_STAGE(bufoff, gbase, voff) do { _Pragma("unroll") for (int _i = 0; _i < 2; ++_i) \
;         __builtin_amdgcn_global_load_lds((const unsigned*)((const char*)(gbase) + (voff)[_i]), (PG8_LAS unsigned*)(lds + (bufoff) + ldsw + _i * 8192), 16, 0, 0); } while (0)
; #define PG8_LDA(dst, b, h) do { _Pragma("unroll") for (int m = 0; m < 4; ++m) _Pragma("unroll") for (int k = 0; k < 2; ++k) dst[m][k] = *(const PG8_LAS bf16x8*)(lds + PG8_SA(b, h) + aoff + m * 2048 + k * 1024); } while (0)
; #define PG8_LDB(dst, b, h) do { _Pragma("unroll") for (int n = 0; n < 2; ++n) _Pragma("unroll") for (int k = 0; k < 2; ++k) dst[n][k] = *(const PG8_LAS bf16x8*)(lds + PG8_SB(b, h) + boff + n * 2048 + k * 1024); } while (0)
; #define PG8_MMA(ai, bj, At, Bt) do { __builtin_amdgcn_s_setprio(1); _Pragma("unroll") for (int m = 0; m < 4; ++m) _Pragma("unroll") for (int n = 0; n < 2; ++n) _Pragma("unroll") for (int k = 0; k < 2; ++k) \
;         acc[ai][bj][m][n] = __builtin_amdgcn_mfma_f32_16x16x32_bf16(Bt[n][k], At[m][k], acc[ai][bj][m][n], 0, 0, 0); __builtin_amdgcn_s_setprio(0); } while (0)
; #define PG8_WAIT_V(n) asm volatile("s_waitcnt vmcnt(" #n ")" ::: "memory")
; #define PG8_WAIT_L(n) asm volatile("s_waitcnt lgkmcnt(" #n ")" ::: "memory")
; #define PG8_BAR __builtin_amdgcn_s_barrier()
; #define PG8_SCHED __builtin_amdgcn_sched_barrier(0)
; template <class Epi, class Sched, bool ALIGN_EPI = false, bool SP2 = false>
; __device__ __forceinline__ void gemm_phase(PG8_LAS unsigned char* lds, const Gemm g, const Sched& S, const Epi& E) {
;     ...
;             PG8_LDB(B0, 0, 0); PG8_LDB(B1, 0, 1); PG8_SCHED; PG8_LDA(At, 0, 0); PG8_STAGE(PG8_SA(1, 1), a1 + hstep, voffA);
;             PG8_WAIT_V(8); PG8_WAIT_L(0); PG8_BAR; PG8_MMA(0, 0, At, B0); PG8_MMA(0, 1, At, B1); PG8_BAR; PG8_SCHED;
;             PG8_LDA(At, 0, 1); PG8_STAGE(PG8_SB(0, 0), b2, voffB); PG8_STAGE(PG8_SB(0, 1), b2 + hstep, voffB); PG8_STAGE(PG8_SA(0, 0), a2, voffA);
;             PG8_WAIT_V(8); PG8_WAIT_L(0); PG8_BAR; PG8_MMA(1, 0, At, B0); PG8_MMA(1, 1, At, B1); PG8_BAR; PG8_SCHED;
	s_setprio 1
	s_waitcnt lgkmcnt(0)
	v_mfma_f32_16x16x32_bf16 v[156:159], v[64:67], v[160:163], v[156:159]
	v_mfma_f32_16x16x32_bf16 v[152:155], v[72:75], v[160:163], v[152:155]
	v_mfma_f32_16x16x32_bf16 v[140:143], v[64:67], v[186:189], v[140:143]
	v_mfma_f32_16x16x32_bf16 v[136:139], v[72:75], v[186:189], v[136:139]
	v_mfma_f32_16x16x32_bf16 v[124:127], v[64:67], v[212:215], v[124:127]
	v_mfma_f32_16x16x32_bf16 v[120:123], v[72:75], v[212:215], v[120:123]
	v_mfma_f32_16x16x32_bf16 v[108:111], v[64:67], v[224:227], v[108:111]
	v_mfma_f32_16x16x32_bf16 v[104:107], v[72:75], v[224:227], v[104:107]
	v_mfma_f32_16x16x32_bf16 v[156:159], v[68:71], v[182:185], v[156:159]
	v_mfma_f32_16x16x32_bf16 v[152:155], v[76:79], v[182:185], v[152:155]
	v_mfma_f32_16x16x32_bf16 v[140:143], v[68:71], v[190:193], v[140:143]
	v_mfma_f32_16x16x32_bf16 v[136:139], v[76:79], v[190:193], v[136:139]
	v_mfma_f32_16x16x32_bf16 v[124:127], v[68:71], v[220:223], v[124:127]
	v_mfma_f32_16x16x32_bf16 v[120:123], v[76:79], v[220:223], v[120:123]
	v_mfma_f32_16x16x32_bf16 v[108:111], v[68:71], v[228:231], v[108:111]
	v_mfma_f32_16x16x32_bf16 v[104:107], v[76:79], v[228:231], v[104:107]
	s_setprio 0
	s_setprio 1
	v_mfma_f32_16x16x32_bf16 v[148:151], v[88:91], v[160:163], v[148:151]
	v_mfma_f32_16x16x32_bf16 v[144:147], v[96:99], v[160:163], v[144:147]
	v_mfma_f32_16x16x32_bf16 v[132:135], v[88:91], v[186:189], v[132:135]
	v_mfma_f32_16x16x32_bf16 v[128:131], v[96:99], v[186:189], v[128:131]
	v_mfma_f32_16x16x32_bf16 v[116:119], v[88:91], v[212:215], v[116:119]
	v_mfma_f32_16x16x32_bf16 v[112:115], v[96:99], v[212:215], v[112:115]
	v_mfma_f32_16x16x32_bf16 v[84:87], v[88:91], v[224:227], v[84:87]
	v_mfma_f32_16x16x32_bf16 v[80:83], v[96:99], v[224:227], v[80:83]
	v_mfma_f32_16x16x32_bf16 v[148:151], v[92:95], v[182:185], v[148:151]
	v_mfma_f32_16x16x32_bf16 v[144:147], v[100:103], v[182:185], v[144:147]
	v_mfma_f32_16x16x32_bf16 v[132:135], v[92:95], v[190:193], v[132:135]
	v_mfma_f32_16x16x32_bf16 v[128:131], v[100:103], v[190:193], v[128:131]
	v_mfma_f32_16x16x32_bf16 v[116:119], v[92:95], v[220:223], v[116:119]
	v_mfma_f32_16x16x32_bf16 v[112:115], v[100:103], v[220:223], v[112:115]
	v_mfma_f32_16x16x32_bf16 v[84:87], v[92:95], v[228:231], v[84:87]
	v_mfma_f32_16x16x32_bf16 v[80:83], v[100:103], v[228:231], v[80:83]
	s_setprio 0
	s_barrier
	s_add_i32 s18, s18, s85
	v_lshl_add_u64 v[164:165], s[6:7], 0, v[208:209]
	s_mov_b32 m0, s18
	ds_read_b128 v[160:163], v218 offset:16384
	ds_read_b128 v[182:185], v218 offset:17408
	ds_read_b128 v[186:189], v218 offset:18432
	ds_read_b128 v[190:193], v218 offset:19456
	ds_read_b128 v[212:215], v218 offset:20480
	ds_read_b128 v[220:223], v218 offset:21504
	ds_read_b128 v[224:227], v218 offset:22528
	ds_read_b128 v[228:231], v218 offset:23552
	global_load_lds_dwordx4 v[164:165], off
	s_add_i32 m0, s18, 0x2000
	s_add_u32 s18, s6, 0x40000
	v_lshl_add_u64 v[194:195], s[6:7], 0, v[170:171]
	s_addc_u32 s19, s7, 0
	s_add_i32 vcc_hi, vcc_hi, s85
	global_load_lds_dwordx4 v[194:195], off
	v_lshl_add_u64 v[232:233], s[18:19], 0, v[208:209]
	s_mov_b32 m0, vcc_hi
	v_lshl_add_u64 v[234:235], s[76:77], 0, v[168:169]
	global_load_lds_dwordx4 v[232:233], off
	v_lshl_add_u64 v[232:233], s[18:19], 0, v[170:171]
	s_add_i32 m0, vcc_hi, 0x2000
	s_nop 0
	global_load_lds_dwordx4 v[232:233], off
	v_lshl_add_u64 v[232:233], s[76:77], 0, v[166:167]
	s_mov_b32 m0, s91
	s_nop 0
	global_load_lds_dwordx4 v[232:233], off
	s_mov_b32 m0, s92
	s_nop 0
	global_load_lds_dwordx4 v[234:235], off
	s_waitcnt vmcnt(63)
	s_waitcnt lgkmcnt(0)
	s_barrier
	s_setprio 1
	s_waitcnt lgkmcnt(0)
	v_mfma_f32_16x16x32_bf16 v[60:63], v[64:67], v[160:163], v[60:63]
	v_mfma_f32_16x16x32_bf16 v[56:59], v[72:75], v[160:163], v[56:59]
	v_mfma_f32_16x16x32_bf16 v[44:47], v[64:67], v[186:189], v[44:47]
	v_mfma_f32_16x16x32_bf16 v[40:43], v[72:75], v[186:189], v[40:43]
	v_mfma_f32_16x16x32_bf16 v[28:31], v[64:67], v[212:215], v[28:31]
	v_mfma_f32_16x16x32_bf16 v[24:27], v[72:75], v[212:215], v[24:27]
	v_mfma_f32_16x16x32_bf16 v[12:15], v[64:67], v[224:227], v[12:15]
	v_mfma_f32_16x16x32_bf16 v[8:11], v[72:75], v[224:227], v[8:11]
	v_mfma_f32_16x16x32_bf16 v[60:63], v[68:71], v[182:185], v[60:63]
	v_mfma_f32_16x16x32_bf16 v[56:59], v[76:79], v[182:185], v[56:59]
	v_mfma_f32_16x16x32_bf16 v[44:47], v[68:71], v[190:193], v[44:47]
	v_mfma_f32_16x16x32_bf16 v[40:43], v[76:79], v[190:193], v[40:43]
	v_mfma_f32_16x16x32_bf16 v[28:31], v[68:71], v[220:223], v[28:31]
	v_mfma_f32_16x16x32_bf16 v[24:27], v[76:79], v[220:223], v[24:27]
	v_mfma_f32_16x16x32_bf16 v[12:15], v[68:71], v[228:231], v[12:15]
	v_mfma_f32_16x16x32_bf16 v[8:11], v[76:79], v[228:231], v[8:11]
	s_setprio 0
	s_setprio 1
	v_mfma_f32_16x16x32_bf16 v[52:55], v[88:91], v[160:163], v[52:55]
	v_mfma_f32_16x16x32_bf16 v[48:51], v[96:99], v[160:163], v[48:51]
	v_mfma_f32_16x16x32_bf16 v[36:39], v[88:91], v[186:189], v[36:39]
	v_mfma_f32_16x16x32_bf16 v[32:35], v[96:99], v[186:189], v[32:35]
	v_mfma_f32_16x16x32_bf16 v[20:23], v[88:91], v[212:215], v[20:23]
	v_mfma_f32_16x16x32_bf16 v[16:19], v[96:99], v[212:215], v[16:19]
	v_mfma_f32_16x16x32_bf16 v[4:7], v[88:91], v[224:227], v[4:7]
	v_mfma_f32_16x16x32_bf16 v[0:3], v[96:99], v[224:227], v[0:3]
	v_mfma_f32_16x16x32_bf16 v[52:55], v[92:95], v[182:185], v[52:55]
	v_mfma_f32_16x16x32_bf16 v[48:51], v[100:103], v[182:185], v[48:51]
	v_mfma_f32_16x16x32_bf16 v[36:39], v[92:95], v[190:193], v[36:39]
	v_mfma_f32_16x16x32_bf16 v[32:35], v[100:103], v[190:193], v[32:35]
	v_mfma_f32_16x16x32_bf16 v[20:23], v[92:95], v[220:223], v[20:23]
	v_mfma_f32_16x16x32_bf16 v[16:19], v[100:103], v[220:223], v[16:19]
	v_mfma_f32_16x16x32_bf16 v[4:7], v[92:95], v[228:231], v[4:7]
	v_mfma_f32_16x16x32_bf16 v[0:3], v[100:103], v[228:231], v[0:3]
	s_setprio 0
	s_barrier
; #define PG8_STAGE(bufoff, gbase, voff) do { _Pragma("unroll") for (int _i = 0; _i < 2; ++_i) \
;         __builtin_amdgcn_global_load_lds((const unsigned*)((const char*)(gbase) + (voff)[_i]), (PG8_LAS unsigned*)(lds + (bufoff) + ldsw + _i * 8192), 16, 0, 0); } while (0)
; #define PG8_LDA(dst, b, h) do { _Pragma("unroll") for (int m = 0; m < 4; ++m) _Pragma("unroll") for (int k = 0; k < 2; ++k) dst[m][k] = *(const PG8_LAS bf16x8*)(lds + PG8_SA(b, h) + aoff + m * 2048 + k * 1024); } while (0)
; #define PG8_LDB(dst, b, h) do { _Pragma("unroll") for (int n = 0; n < 2; ++n) _Pragma("unroll") for (int k = 0; k < 2; ++k) dst[n][k] = *(const PG8_LAS bf16x8*)(lds + PG8_SB(b, h) + boff + n * 2048 + k * 1024); } while (0)
; #define PG8_MMA(ai, bj, At, Bt) do { __builtin_amdgcn_s_setprio(1); _Pragma("unroll") for (int m = 0; m < 4; ++m) _Pragma("unroll") for (int n = 0; n < 2; ++n) _Pragma("unroll") for (int k = 0; k < 2; ++k) \
;         acc[ai][bj][m][n] = __builtin_amdgcn_mfma_f32_16x16x32_bf16(Bt[n][k], At[m][k], acc[ai][bj][m][n], 0, 0, 0); __builtin_amdgcn_s_setprio(0); } while (0)
; #define PG8_WAIT_V(n) asm volatile("s_waitcnt vmcnt(" #n ")" ::: "memory")
; #define PG8_WAIT_L(n) asm volatile("s_waitcnt lgkmcnt(" #n ")" ::: "memory")
; #define PG8_BAR __builtin_amdgcn_s_barrier()
; #define PG8_SCHED __builtin_amdgcn_sched_barrier(0)
; template <class Epi, class Sched, bool ALIGN_EPI = false, bool SP2 = false>
; __device__ __forceinline__ void gemm_phase(PG8_LAS unsigned char* lds, const Gemm g, const Sched& S, const Epi& E) {
;     ...
;             PG8_LDB(B0, 1, 0); PG8_LDB(B1, 1, 1); PG8_SCHED; PG8_LDA(At, 1, 0); PG8_STAGE(PG8_SA(0, 1), a2 + hstep, voffA);
;             PG8_WAIT_V(8); PG8_WAIT_L(0); PG8_BAR; PG8_MMA(0, 0, At, B0); PG8_MMA(0, 1, At, B1); PG8_BAR; PG8_SCHED;
	s_add_i32 vcc_hi, 0, 0x18000
	s_add_i32 s34, 0, 0x1c000
	v_add_u32_e32 v76, vcc_hi, v196
	v_add_u32_e32 v100, s34, v196
	ds_read_b128 v[64:67], v76
	ds_read_b128 v[68:71], v76 offset:1024
	ds_read_b128 v[72:75], v76 offset:2048
	ds_read_b128 v[76:79], v76 offset:3072
	ds_read_b128 v[88:91], v100
	ds_read_b128 v[92:95], v100 offset:1024
	ds_read_b128 v[96:99], v100 offset:2048
	ds_read_b128 v[100:103], v100 offset:3072
	s_add_u32 s18, s76, 0x40000
	s_addc_u32 s19, s77, 0
	s_mov_b32 m0, s93
	v_lshl_add_u64 v[236:237], s[18:19], 0, v[166:167]
	ds_read_b128 v[160:163], v218 offset:32768
	ds_read_b128 v[182:185], v218 offset:33792
	ds_read_b128 v[186:189], v218 offset:34816
	ds_read_b128 v[190:193], v218 offset:35840
	ds_read_b128 v[212:215], v218 offset:36864
	ds_read_b128 v[220:223], v218 offset:37888
	ds_read_b128 v[224:227], v218 offset:38912
	ds_read_b128 v[228:231], v218 offset:39936
	global_load_lds_dwordx4 v[236:237], off
	v_lshl_add_u64 v[236:237], s[18:19], 0, v[168:169]
	s_mov_b32 m0, s94
	s_nop 0
	global_load_lds_dwordx4 v[236:237], off
	s_waitcnt vmcnt(10)
	s_waitcnt lgkmcnt(0)
	s_barrier
	s_setprio 1
	s_waitcnt lgkmcnt(0)
	v_mfma_f32_16x16x32_bf16 v[156:159], v[64:67], v[160:163], v[156:159]
	v_mfma_f32_16x16x32_bf16 v[152:155], v[72:75], v[160:163], v[152:155]
	v_mfma_f32_16x16x32_bf16 v[140:143], v[64:67], v[186:189], v[140:143]
	v_mfma_f32_16x16x32_bf16 v[136:139], v[72:75], v[186:189], v[136:139]
	v_mfma_f32_16x16x32_bf16 v[124:127], v[64:67], v[212:215], v[124:127]
	v_mfma_f32_16x16x32_bf16 v[120:123], v[72:75], v[212:215], v[120:123]
	v_mfma_f32_16x16x32_bf16 v[108:111], v[64:67], v[224:227], v[108:111]
	v_mfma_f32_16x16x32_bf16 v[104:107], v[72:75], v[224:227], v[104:107]
	v_mfma_f32_16x16x32_bf16 v[156:159], v[68:71], v[182:185], v[156:159]
	v_mfma_f32_16x16x32_bf16 v[152:155], v[76:79], v[182:185], v[152:155]
	v_mfma_f32_16x16x32_bf16 v[140:143], v[68:71], v[190:193], v[140:143]
	v_mfma_f32_16x16x32_bf16 v[136:139], v[76:79], v[190:193], v[136:139]
	v_mfma_f32_16x16x32_bf16 v[124:127], v[68:71], v[220:223], v[124:127]
	v_mfma_f32_16x16x32_bf16 v[120:123], v[76:79], v[220:223], v[120:123]
	v_mfma_f32_16x16x32_bf16 v[108:111], v[68:71], v[228:231], v[108:111]
	v_mfma_f32_16x16x32_bf16 v[104:107], v[76:79], v[228:231], v[104:107]
	s_setprio 0
	s_setprio 1
	v_mfma_f32_16x16x32_bf16 v[148:151], v[88:91], v[160:163], v[148:151]
	v_mfma_f32_16x16x32_bf16 v[144:147], v[96:99], v[160:163], v[144:147]
	v_mfma_f32_16x16x32_bf16 v[132:135], v[88:91], v[186:189], v[132:135]
	v_mfma_f32_16x16x32_bf16 v[128:131], v[96:99], v[186:189], v[128:131]
	v_mfma_f32_16x16x32_bf16 v[116:119], v[88:91], v[212:215], v[116:119]
	v_mfma_f32_16x16x32_bf16 v[112:115], v[96:99], v[212:215], v[112:115]
	v_mfma_f32_16x16x32_bf16 v[84:87], v[88:91], v[224:227], v[84:87]
	v_mfma_f32_16x16x32_bf16 v[80:83], v[96:99], v[224:227], v[80:83]
	v_mfma_f32_16x16x32_bf16 v[148:151], v[92:95], v[182:185], v[148:151]
	v_mfma_f32_16x16x32_bf16 v[144:147], v[100:103], v[182:185], v[144:147]
	v_mfma_f32_16x16x32_bf16 v[132:135], v[92:95], v[190:193], v[132:135]
	v_mfma_f32_16x16x32_bf16 v[128:131], v[100:103], v[190:193], v[128:131]
	v_mfma_f32_16x16x32_bf16 v[116:119], v[92:95], v[220:223], v[116:119]
	v_mfma_f32_16x16x32_bf16 v[112:115], v[100:103], v[220:223], v[112:115]
	v_mfma_f32_16x16x32_bf16 v[84:87], v[92:95], v[228:231], v[84:87]
	v_mfma_f32_16x16x32_bf16 v[80:83], v[100:103], v[228:231], v[80:83]
	s_setprio 0
	s_barrier
; #define PG8_STAGE(bufoff, gbase, voff) do { _Pragma("unroll") for (int _i = 0; _i < 2; ++_i) \
;         __builtin_amdgcn_global_load_lds((const unsigned*)((const char*)(gbase) + (voff)[_i]), (PG8_LAS unsigned*)(lds + (bufoff) + ldsw + _i * 8192), 16, 0, 0); } while (0)
; #define PG8_LDA(dst, b, h) do { _Pragma("unroll") for (int m = 0; m < 4; ++m) _Pragma("unroll") for (int k = 0; k < 2; ++k) dst[m][k] = *(const PG8_LAS bf16x8*)(lds + PG8_SA(b, h) + aoff + m * 2048 + k * 1024); } while (0)
; #define PG8_MMA(ai, bj, At, Bt) do { __builtin_amdgcn_s_setprio(1); _Pragma("unroll") for (int m = 0; m < 4; ++m) _Pragma("unroll") for (int n = 0; n < 2; ++n) _Pragma("unroll") for (int k = 0; k < 2; ++k) \
;         acc[ai][bj][m][n] = __builtin_amdgcn_mfma_f32_16x16x32_bf16(Bt[n][k], At[m][k], acc[ai][bj][m][n], 0, 0, 0); __builtin_amdgcn_s_setprio(0); } while (0)
; #define PG8_WAIT_V(n) asm volatile("s_waitcnt vmcnt(" #n ")" ::: "memory")
; #define PG8_WAIT_L(n) asm volatile("s_waitcnt lgkmcnt(" #n ")" ::: "memory")
; #define PG8_BAR __builtin_amdgcn_s_barrier()
; #define PG8_SCHED __builtin_amdgcn_sched_barrier(0)
; template <class Epi, class Sched, bool ALIGN_EPI = false, bool SP2 = false>
; __device__ __forceinline__ void gemm_phase(PG8_LAS unsigned char* lds, const Gemm g, const Sched& S, const Epi& E) {
;     ...
;         for (int t = 0; t < nt; t += 2) {
;     ...
;             PG8_LDA(At, 1, 1); PG8_STAGE(PG8_SB(1, 0), b3, voffB); PG8_STAGE(PG8_SB(1, 1), b3 + hstep, voffB); PG8_STAGE(PG8_SA(1, 0), a3, voffA);
;             PG8_WAIT_V(8); PG8_WAIT_L(0); PG8_BAR; PG8_MMA(1, 0, At, B0); PG8_MMA(1, 1, At, B1); PG8_BAR; PG8_SCHED;
	s_add_i32 s18, vcc_hi, s85
	v_lshl_add_u64 v[164:165], v[164:165], 0, s[24:25]
	s_mov_b32 m0, s18
	ds_read_b128 v[160:163], v218 offset:49152
	ds_read_b128 v[182:185], v218 offset:50176
	ds_read_b128 v[186:189], v218 offset:51200
	ds_read_b128 v[190:193], v218 offset:52224
	ds_read_b128 v[212:215], v218 offset:53248
	ds_read_b128 v[220:223], v218 offset:54272
	ds_read_b128 v[224:227], v218 offset:55296
	ds_read_b128 v[228:231], v218 offset:56320
	global_load_lds_dwordx4 v[164:165], off
	s_add_i32 m0, s18, 0x2000
	s_add_u32 s6, s6, 0x40080
	v_lshl_add_u64 v[164:165], v[194:195], 0, s[24:25]
	s_addc_u32 s7, s7, 0
	s_add_i32 s18, s34, s85
	global_load_lds_dwordx4 v[164:165], off
	v_lshl_add_u64 v[164:165], s[6:7], 0, v[208:209]
	s_mov_b32 m0, s18
	s_nop 0
	global_load_lds_dwordx4 v[164:165], off
	v_lshl_add_u64 v[164:165], s[6:7], 0, v[170:171]
	s_add_i32 m0, s18, 0x2000
	s_nop 0
	global_load_lds_dwordx4 v[164:165], off
	v_lshl_add_u64 v[164:165], v[232:233], 0, s[24:25]
	s_mov_b32 m0, s95
	s_nop 0
	global_load_lds_dwordx4 v[164:165], off
	v_lshl_add_u64 v[164:165], v[234:235], 0, s[24:25]
	s_mov_b32 m0, s96
	s_nop 0
	global_load_lds_dwordx4 v[164:165], off
	s_waitcnt vmcnt(8)
	s_waitcnt lgkmcnt(0)
	s_barrier
	s_setprio 1
	s_waitcnt lgkmcnt(0)
	v_mfma_f32_16x16x32_bf16 v[60:63], v[64:67], v[160:163], v[60:63]
	v_mfma_f32_16x16x32_bf16 v[56:59], v[72:75], v[160:163], v[56:59]
	v_mfma_f32_16x16x32_bf16 v[44:47], v[64:67], v[186:189], v[44:47]
	v_mfma_f32_16x16x32_bf16 v[40:43], v[72:75], v[186:189], v[40:43]
	v_mfma_f32_16x16x32_bf16 v[28:31], v[64:67], v[212:215], v[28:31]
	v_mfma_f32_16x16x32_bf16 v[24:27], v[72:75], v[212:215], v[24:27]
	v_mfma_f32_16x16x32_bf16 v[12:15], v[64:67], v[224:227], v[12:15]
	v_mfma_f32_16x16x32_bf16 v[8:11], v[72:75], v[224:227], v[8:11]
	v_mfma_f32_16x16x32_bf16 v[60:63], v[68:71], v[182:185], v[60:63]
	v_mfma_f32_16x16x32_bf16 v[56:59], v[76:79], v[182:185], v[56:59]
	v_mfma_f32_16x16x32_bf16 v[44:47], v[68:71], v[190:193], v[44:47]
	v_mfma_f32_16x16x32_bf16 v[40:43], v[76:79], v[190:193], v[40:43]
	v_mfma_f32_16x16x32_bf16 v[28:31], v[68:71], v[220:223], v[28:31]
	v_mfma_f32_16x16x32_bf16 v[24:27], v[76:79], v[220:223], v[24:27]
	v_mfma_f32_16x16x32_bf16 v[12:15], v[68:71], v[228:231], v[12:15]
	v_mfma_f32_16x16x32_bf16 v[8:11], v[76:79], v[228:231], v[8:11]
	s_setprio 0
	s_setprio 1
	v_mfma_f32_16x16x32_bf16 v[52:55], v[88:91], v[160:163], v[52:55]
	v_mfma_f32_16x16x32_bf16 v[48:51], v[96:99], v[160:163], v[48:51]
	v_mfma_f32_16x16x32_bf16 v[36:39], v[88:91], v[186:189], v[36:39]
	v_mfma_f32_16x16x32_bf16 v[32:35], v[96:99], v[186:189], v[32:35]
	v_mfma_f32_16x16x32_bf16 v[20:23], v[88:91], v[212:215], v[20:23]
	v_mfma_f32_16x16x32_bf16 v[16:19], v[96:99], v[212:215], v[16:19]
	v_mfma_f32_16x16x32_bf16 v[4:7], v[88:91], v[224:227], v[4:7]
	v_mfma_f32_16x16x32_bf16 v[0:3], v[96:99], v[224:227], v[0:3]
	v_mfma_f32_16x16x32_bf16 v[52:55], v[92:95], v[182:185], v[52:55]
	v_mfma_f32_16x16x32_bf16 v[48:51], v[100:103], v[182:185], v[48:51]
	v_mfma_f32_16x16x32_bf16 v[36:39], v[92:95], v[190:193], v[36:39]
	v_mfma_f32_16x16x32_bf16 v[32:35], v[100:103], v[190:193], v[32:35]
	v_mfma_f32_16x16x32_bf16 v[20:23], v[92:95], v[220:223], v[20:23]
	v_mfma_f32_16x16x32_bf16 v[16:19], v[100:103], v[220:223], v[16:19]
	v_mfma_f32_16x16x32_bf16 v[4:7], v[92:95], v[228:231], v[4:7]
	v_mfma_f32_16x16x32_bf16 v[0:3], v[100:103], v[228:231], v[0:3]
	s_setprio 0
	s_barrier
	s_add_i32 vcc_lo, vcc_lo, 2
	s_add_u32 s4, s4, 0x100
	s_addc_u32 s5, s5, 0
	s_add_u32 s78, s78, 0x100
	s_addc_u32 s79, s79, 0
	s_cmp_gt_u32 vcc_lo, 13
